# P2 qkv GEMM tile order: each XCD's tile list rotated so the partial third round takes the cheap V-head tiles (plain epilogue) instead of rotary q-head tiles
# speedup vs baseline: 1.0540x; 1.0040x over previous
;     ...
;     for (int i = F.tid; i < 1024; i += NWAVES * 64) {
;         gl[i] = gw_[i];
; #pragma unroll
;         for (int cnd = 0; cnd < 3; ++cnd) {
;             float sh, sc;
;             if (from_partials) { sh = ada_b[layer * 6144 + offsh + i]; sc = ada_b[layer * 6144 + offsc + i];
;                 float ph[ADA_KS], pc[ADA_KS];
; #pragma unroll
;                 for (int ks = 0; ks < ADA_KS; ++ks) { const float* p = modp + ((size_t)(ks * 2 + layer) * 3 + cnd) * 6144; ph[ks] = p[offsh + i]; pc[ks] = p[offsc + i]; }
; #pragma unroll
;                 for (int ks = 0; ks < ADA_KS; ++ks) { sh += ph[ks]; sc += pc[ks]; } }
;             else { sh = mod[(layer * 3 + cnd) * 6144 + offsh + i]; sc = mod[(layer * 3 + cnd) * 6144 + offsc + i]; }
;             scl[cnd * 1024 + i] = 1.f + sc; shl[cnd * 1024 + i] = sh;
;         }
;     }
.LBB0_187:
	v_lshlrev_b32_e32 v220, 2, v2
	v_lshlrev_b32_e32 v221, 2, v3
	global_load_dword v236, v220, s[0:1]
	global_load_dword v237, v221, s[0:1]
	v_add_u32_e32 v222, s14, v220
	v_add_u32_e32 v223, s14, v221
	global_load_dword v228, v222, s[10:11] offset:-4096
	global_load_dword v229, v223, s[10:11] offset:-4096
	global_load_dword v230, v222, s[10:11]
	global_load_dword v231, v223, s[10:11]
	v_add_u32_e32 v222, s15, v220
	v_add_u32_e32 v223, s15, v221
	global_load_dword v232, v222, s[10:11] offset:-4096
	global_load_dword v233, v223, s[10:11] offset:-4096
	global_load_dword v234, v222, s[10:11]
	global_load_dword v235, v223, s[10:11]
	v_add_u32_e32 v222, s16, v220
	v_add_u32_e32 v223, s16, v221
	global_load_dword v238, v222, s[10:11] offset:-4096
	global_load_dword v239, v223, s[10:11] offset:-4096
	global_load_dword v240, v222, s[10:11]
	global_load_dword v241, v223, s[10:11]
	v_add_u32_e32 v5, -2, v5
	v_add_u32_e32 v224, 0x400, v2
	v_add_u32_e32 v225, 0x400, v3
	v_lshl_add_u32 v226, v224, 2, 0
	v_lshl_add_u32 v227, v225, 2, 0
	v_cmp_eq_u32_e32 vcc, 0, v5
	s_or_b64 s[12:13], vcc, s[12:13]
	s_waitcnt vmcnt(0)
	ds_write2st64_b32 v6, v236, v237 offset1:8
	v_add_f32_e32 v230, 1.0, v230
	v_add_f32_e32 v231, 1.0, v231
	ds_write2st64_b32 v6, v230, v231 offset0:16 offset1:24
	ds_write2st64_b32 v6, v228, v229 offset0:64 offset1:72
	v_add_f32_e32 v234, 1.0, v234
	v_add_f32_e32 v235, 1.0, v235
	ds_write_b32 v226, v234 offset:4096
	ds_write_b32 v227, v235 offset:4096
	ds_write_b32 v226, v232 offset:16384
	ds_write_b32 v227, v233 offset:16384
	v_add_f32_e32 v240, 1.0, v240
	v_add_f32_e32 v241, 1.0, v241
	ds_write_b32 v220, v240 offset:12288
	ds_write_b32 v221, v241 offset:12288
	ds_write_b32 v220, v238 offset:24576
	ds_write_b32 v221, v239 offset:24576
	v_add_u32_e32 v6, 0x1000, v6
	v_mov_b32_e32 v2, v224
	v_mov_b32_e32 v3, v225
	s_andn2_b64 exec, exec, s[12:13]
	s_cbranch_execnz .LBB0_187
	s_nop 0
	s_nop 0
	s_nop 0
	s_nop 0
	s_nop 0
	s_or_b64 exec, exec, s[12:13]
	v_cmp_ne_u32_e32 vcc, v0, v4
	v_lshl_add_u32 v2, v4, 9, v170
	s_orn2_b64 s[10:11], vcc, exec

;     __host__ __device__ bool next(int i, Unit& u) const {
;     ...
;         int wgid = (int)L; { const int q = nwg / NXCD, r = nwg % NXCD, xcd = wgid % NXCD, off = wgid / NXCD; wgid = (xcd < r ? xcd * (q + 1) : r * (q + 1) + (xcd - r) * q) + off; }
;         const int nig = WGM * nN, gid = wgid / nig, fm = gid * WGM, gsz = (nM - fm) < WGM ? (nM - fm) : WGM;
;         u.pm = fm + ((wgid % nig) % gsz); u.pn = (wgid % nig) / gsz; u.kinfo = ntK << 8; return true;
.LBB0_495:
	s_lshl_b32 s2, s48, 3
	v_cvt_f32_u32_e32 v2, s2
	s_ashr_i32 s3, s4, 3
	s_sub_i32 s4, 0, s2
	s_cmpk_lg_u32 s50, 0x252
	s_cbranch_scc1 .Lrot_skip_a
	s_min_u32 s11, s6, 2
	s_sub_i32 s3, s3, s11
	s_sub_i32 s3, s3, s6
	s_sub_i32 s3, s3, s6
	s_sub_i32 s3, s3, 8
	s_cmp_lt_i32 s3, 0
	s_cbranch_scc0 .Lrot_skip_a
	s_add_i32 s3, s3, s9
	s_cmp_lt_i32 s6, s10
	s_cbranch_scc0 .Lrot_skip_a
	s_add_i32 s3, s3, 1
.Lrot_skip_a:
	s_add_i32 s3, s5, s3
	v_rcp_iflag_f32_e32 v2, v2
	s_abs_i32 s6, s3
	s_ashr_i32 s5, s3, 31
	v_mul_f32_e32 v2, 0x4f7ffffe, v2
	v_cvt_u32_f32_e32 v2, v2
	s_nop 0
	v_readfirstlane_b32 s7, v2
	s_mul_i32 s4, s4, s7
	s_mul_hi_u32 s4, s7, s4
	s_add_i32 s7, s7, s4
	s_mul_hi_u32 s4, s6, s7
	s_mul_i32 s7, s4, s2
	s_sub_i32 s6, s6, s7
	s_add_i32 s9, s4, 1
	s_sub_i32 s7, s6, s2
	s_cmp_ge_u32 s6, s2
	s_cselect_b32 s4, s9, s4
	s_cselect_b32 s6, s7, s6
	s_add_i32 s7, s4, 1
	s_cmp_ge_u32 s6, s2
	s_cselect_b32 s4, s7, s4
	s_xor_b32 s4, s4, s5
	s_sub_i32 s4, s4, s5
	s_lshl_b32 s5, s4, 3
	s_mul_i32 s4, s4, s2
	s_sub_i32 s2, s69, s5
	s_min_i32 s6, s2, 8
	s_sext_i32_i16 s2, s6
	v_cvt_f32_i32_e32 v2, s2
	s_sub_i32 s4, s3, s4
	s_sext_i32_i16 s3, s4
	v_cvt_f32_i32_e32 v3, s3
	v_rcp_iflag_f32_e32 v13, v2
	s_xor_b32 s2, s3, s2
	s_ashr_i32 s2, s2, 30
	s_or_b32 s7, s2, 1
	v_mul_f32_e32 v13, v3, v13
	v_trunc_f32_e32 v13, v13
	v_fma_f32 v3, -v13, v2, v3
	v_cvt_i32_f32_e32 v13, v13
	v_cmp_ge_f32_e64 s[2:3], |v3|, |v2|
	s_and_b64 s[2:3], s[2:3], exec
	s_cselect_b32 s2, s7, 0
	v_readfirstlane_b32 s3, v13
	s_add_i32 s2, s3, s2
	s_sext_i32_i16 s76, s2
	s_mul_i32 s2, s2, s6
	s_sub_i32 s2, s4, s2
	s_sext_i32_i16 s2, s2
	s_add_i32 s40, s5, s2
	s_lshl_b32 s43, s54, 2
	s_mov_b64 s[4:5], -1

;     __host__ __device__ bool next(int i, Unit& u) const {
;     ...
;         int wgid = (int)L; { const int q = nwg / NXCD, r = nwg % NXCD, xcd = wgid % NXCD, off = wgid / NXCD; wgid = (xcd < r ? xcd * (q + 1) : r * (q + 1) + (xcd - r) * q) + off; }
;         const int nig = WGM * nN, gid = wgid / nig, fm = gid * WGM, gsz = (nM - fm) < WGM ? (nM - fm) : WGM;
;         u.pm = fm + ((wgid % nig) % gsz); u.pn = (wgid % nig) / gsz; u.kinfo = ntK << 8; return true;
.LBB0_512:
	s_ashr_i32 s0, s4, 3
	s_cmpk_lg_u32 s50, 0x252
	s_cbranch_scc1 .Lrot_skip_b
	s_min_u32 s1, s5, 2
	s_sub_i32 s0, s0, s1
	s_sub_i32 s0, s0, s5
	s_sub_i32 s0, s0, s5
	s_sub_i32 s0, s0, 8
	s_cmp_lt_i32 s0, 0
	s_cbranch_scc0 .Lrot_skip_b
	v_readlane_b32 s1, v243, 49
	s_add_i32 s0, s0, s1
	s_cmp_lt_i32 s5, s53
	s_cbranch_scc0 .Lrot_skip_b
	s_add_i32 s0, s0, 1
.Lrot_skip_b:
	s_add_i32 s0, s8, s0
	s_abs_i32 s4, s0
	v_readlane_b32 s5, v243, 43
	s_mul_hi_u32 s5, s4, s5
	s_mul_i32 s8, s5, s91
	s_sub_i32 s4, s4, s8
	s_ashr_i32 s1, s0, 31
	s_add_i32 s8, s5, 1
	s_sub_i32 s9, s4, s91
	s_cmp_ge_u32 s4, s91
	s_cselect_b32 s5, s8, s5
	s_cselect_b32 s4, s9, s4
	s_add_i32 s8, s5, 1
	s_cmp_ge_u32 s4, s91
	s_cselect_b32 s4, s8, s5
	s_xor_b32 s4, s4, s1
	s_sub_i32 s1, s4, s1
	s_lshl_b32 s4, s1, 3
	s_sub_i32 s5, s69, s4
	s_min_i32 s5, s5, 8
	s_abs_i32 s8, s5
	v_cvt_f32_u32_e32 v0, s8
	s_sub_i32 s10, 0, s8
	s_mul_i32 s1, s1, s91
	s_sub_i32 s0, s0, s1
	v_rcp_iflag_f32_e32 v0, v0
	s_abs_i32 s1, s0
	s_xor_b32 s9, s0, s5
	s_ashr_i32 s9, s9, 31
	v_mul_f32_e32 v0, 0x4f7ffffe, v0
	v_cvt_u32_f32_e32 v0, v0
	v_readlane_b32 s41, v243, 42
	v_readfirstlane_b32 s11, v0
	s_mul_i32 s10, s10, s11
	s_mul_hi_u32 s10, s11, s10
	s_add_i32 s11, s11, s10
	s_mul_hi_u32 s10, s1, s11
	s_mul_i32 s11, s10, s8
	s_sub_i32 s1, s1, s11
	s_add_i32 s11, s10, 1
	s_sub_i32 s12, s1, s8
	s_cmp_ge_u32 s1, s8
	s_cselect_b32 s10, s11, s10
	s_cselect_b32 s1, s12, s1
	s_add_i32 s11, s10, 1
	s_cmp_ge_u32 s1, s8
	s_cselect_b32 s1, s11, s10
	s_xor_b32 s1, s1, s9
	s_sub_i32 s88, s1, s9
	s_mul_i32 s1, s88, s5
	s_sub_i32 s0, s0, s1
	s_add_i32 s42, s0, s4
	s_mov_b64 s[8:9], -1
